# B3 row loop: software L2 prefetch of the row after next, guard waits hoisted (on v025)
# baseline (speedup 1.0000x reference)
; #define TIDX (tid_launder())
; DI unsigned pack2(float a, float b) { hwf2 v = {a, b}; hwbf2 r = __builtin_convertvector(v, hwbf2); return __builtin_bit_cast(unsigned, r); }
; DI void phaseB3(const Params& p, int l) {
;   const int lane = TIDX & 63, wid = TIDX >> 6;
;   const float* g = p.b_out_norm + l * 128;
;   const int d0 = (lane & 15) * 8;
;   float gq[8];
; #pragma unroll
;   for (int i = 0; i < 8; ++i) gq[i] = g[d0 + i];
;   const int tstep = gridDim.x * 4;
;   int t = blockIdx.x * 4 + wid;
;   uint4 nov = make_uint4(0, 0, 0, 0), nzv = make_uint4(0, 0, 0, 0);
;   if (t < T_TOK) { nov = *(const uint4*)(p.ob + (size_t)t * 512 + lane * 8); nzv = *(const uint4*)(p.projZ + (size_t)t * LDA_Z + 256 + lane * 8); }
; #pragma unroll 1
;   for (; t < T_TOK; t += tstep) {
;     const uint4 ov = nov, zv = nzv;
;     const int tn = t + tstep < T_TOK ? t + tstep : t;
;     nov = *(const uint4*)(p.ob + (size_t)tn * 512 + lane * 8); nzv = *(const uint4*)(p.projZ + (size_t)tn * LDA_Z + 256 + lane * 8);
;     float v[8], z[8];
;     v[0] = __uint_as_float(ov.x << 16); v[1] = __uint_as_float(ov.x & 0xffff0000u);
;     v[2] = __uint_as_float(ov.y << 16); v[3] = __uint_as_float(ov.y & 0xffff0000u);
;     v[4] = __uint_as_float(ov.z << 16); v[5] = __uint_as_float(ov.z & 0xffff0000u);
;     v[6] = __uint_as_float(ov.w << 16); v[7] = __uint_as_float(ov.w & 0xffff0000u);
;     z[0] = __uint_as_float(zv.x << 16); z[1] = __uint_as_float(zv.x & 0xffff0000u);
;     z[2] = __uint_as_float(zv.y << 16); z[3] = __uint_as_float(zv.y & 0xffff0000u);
;     z[4] = __uint_as_float(zv.z << 16); z[5] = __uint_as_float(zv.z & 0xffff0000u);
;     z[6] = __uint_as_float(zv.w << 16); z[7] = __uint_as_float(zv.w & 0xffff0000u);
;     float ss = 0.f;
; #pragma unroll
;     for (int i = 0; i < 8; ++i) ss += v[i] * v[i];
; #pragma unroll
;     for (int o = 8; o >= 1; o >>= 1) ss += __shfl_xor(ss, o);
;     const float rr = rsqrtf(ss * (1.f / 128.f) + 1e-6f);
;     float y[8];
; #pragma unroll
;     for (int i = 0; i < 8; ++i) y[i] = v[i] * rr * gq[i] * z[i];
;     uint4 w; w.x = pack2(y[0], y[1]); w.y = pack2(y[2], y[3]); w.z = pack2(y[4], y[5]); w.w = pack2(y[6], y[7]);
;     *(uint4*)(p.projZ + (size_t)t * LDA_Z + 256 + lane * 8) = w;
;   }
.LBB0_84:
	s_or_b64 exec, exec, s[38:39]
	v_mov_b32_e32 v24, v230
	v_mov_b32_e32 v0, v230
	v_readlane_b32 s0, v250, 61
	v_ashrrev_i32_e32 v0, 6, v0
	s_nop 0
	v_add_u32_e32 v18, s0, v0
	v_cmp_gt_i32_e32 vcc, s51, v18
	s_and_saveexec_b64 s[0:1], vcc
	s_mov_b32 s14, 0x800000
	s_cbranch_execz .LBB0_87
	v_readlane_b32 s16, v250, 18
	v_readlane_b32 s2, v253, 63
	v_readlane_b32 s17, v250, 19
	v_readlane_b32 s3, v254, 0
	v_readlane_b32 s18, v250, 20
	v_readlane_b32 s19, v250, 21
	v_readlane_b32 s20, v250, 22
	v_readlane_b32 s21, v250, 23
	v_readlane_b32 s22, v250, 24
	v_readlane_b32 s23, v250, 25
	v_readlane_b32 s24, v250, 26
	v_readlane_b32 s25, v250, 27
	s_mov_b64 s[4:5], s[16:17]
	s_lshl_b64 s[2:3], s[2:3], 2
	s_mov_b64 s[8:9], s[20:21]
	v_readlane_b32 s26, v250, 28
	v_readlane_b32 s27, v250, 29
	v_readlane_b32 s28, v250, 30
	v_readlane_b32 s29, v250, 31
	v_readlane_b32 s30, v250, 32
	v_readlane_b32 s31, v250, 33
	s_mov_b64 s[6:7], s[18:19]
	s_mov_b64 s[10:11], s[22:23]
	s_add_u32 s2, s8, s2
	v_lshlrev_b32_e32 v0, 5, v24
	s_mov_b64 s[12:13], s[24:25]
	s_addc_u32 s3, s9, s3
	v_and_b32_e32 v0, 0x1e0, v0
	v_ashrrev_i32_e32 v19, 31, v18
	v_readlane_b32 s4, v253, 34
	v_readlane_b32 s16, v252, 57
	global_load_dwordx4 v[2:5], v0, s[2:3] offset:16
	global_load_dwordx4 v[6:9], v0, s[2:3]
	v_lshlrev_b64 v[10:11], 10, v[18:19]
	v_readlane_b32 s10, v253, 40
	v_readlane_b32 s11, v253, 41
	v_lshlrev_b32_e32 v0, 4, v24
	v_lshlrev_b64 v[30:31], 11, v[18:19]
	v_readlane_b32 s28, v253, 5
	v_readlane_b32 s29, v253, 6
	v_lshl_add_u64 v[10:11], s[10:11], 0, v[10:11]
	v_and_b32_e32 v0, 0x3f0, v0
	v_lshl_add_u64 v[14:15], s[28:29], 0, v[30:31]
	v_lshl_add_u64 v[10:11], v[10:11], 0, v[0:1]
	v_lshl_add_u64 v[14:15], v[14:15], 0, v[0:1]
	global_load_dwordx4 v[10:13], v[10:11], off
	v_and_b32_e32 v19, 64, v249
	global_load_dwordx4 v[14:17], v[14:15], off offset:512
	v_add_u32_e32 v20, 64, v19
	v_xor_b32_e32 v19, 8, v249
	v_cmp_lt_i32_e32 vcc, v19, v20
	v_xor_b32_e32 v21, 4, v249
	v_lshl_add_u64 v[22:23], s[28:29], 0, v[0:1]
	v_cndmask_b32_e32 v19, v249, v19, vcc
	v_cmp_lt_i32_e32 vcc, v21, v20
	v_readlane_b32 s2, v253, 9
	v_readlane_b32 s3, v253, 10
	v_cndmask_b32_e32 v21, v249, v21, vcc
	v_lshlrev_b32_e32 v26, 2, v21
	v_xor_b32_e32 v21, 2, v249
	v_cmp_lt_i32_e32 vcc, v21, v20
	v_lshlrev_b32_e32 v19, 2, v19
	v_readlane_b32 s5, v253, 35
	v_cndmask_b32_e32 v21, v249, v21, vcc
	v_lshlrev_b32_e32 v27, 2, v21
	v_xor_b32_e32 v21, 1, v249
	v_cmp_lt_i32_e32 vcc, v21, v20
	v_readlane_b32 s6, v253, 36
	v_readlane_b32 s7, v253, 37
	v_cndmask_b32_e32 v20, v249, v21, vcc
	v_lshlrev_b32_e32 v28, 2, v20
	v_lshl_add_u64 v[20:21], s[10:11], 0, v[0:1]
	v_and_b32_e32 v0, 63, v24
	v_lshl_or_b32 v30, v0, 4, v30
	v_lshl_add_u64 v[24:25], s[2:3], 0, v[30:31]
	s_mov_b64 s[2:3], 0
	v_readlane_b32 s8, v253, 38
	v_readlane_b32 s9, v253, 39
	v_readlane_b32 s17, v252, 58
	v_readlane_b32 s18, v252, 59
	v_readlane_b32 s19, v252, 60
	v_readlane_b32 s20, v252, 61
	v_readlane_b32 s21, v252, 62
	v_readlane_b32 s22, v252, 63
	v_readlane_b32 s23, v253, 0
	v_readlane_b32 s24, v253, 1
	v_readlane_b32 s25, v253, 2
	v_readlane_b32 s26, v253, 3
	v_readlane_b32 s27, v253, 4
	v_readlane_b32 s30, v253, 7
	v_readlane_b32 s31, v253, 8
	s_waitcnt vmcnt(0)
.LBB0_86:
	v_add_u32_e32 v0, s94, v18
	v_cmp_gt_i32_e32 vcc, s51, v0
	v_lshlrev_b32_e32 v38, 16, v10
	v_and_b32_e32 v39, 0xffff0000, v10
	v_cndmask_b32_e32 v30, v18, v0, vcc
	v_ashrrev_i32_e32 v31, 31, v30
	v_lshlrev_b64 v[32:33], 10, v[30:31]
	v_lshlrev_b64 v[30:31], 11, v[30:31]
	v_lshl_add_u64 v[32:33], v[20:21], 0, v[32:33]
	v_lshl_add_u64 v[34:35], v[22:23], 0, v[30:31]
	global_load_dwordx4 v[30:33], v[32:33], off
	s_nop 0
	global_load_dwordx4 v[34:37], v[34:35], off offset:512
	v_add_u32_e32 v54, s94, v0
	v_min_i32_e32 v54, s46, v54
	v_ashrrev_i32_e32 v55, 31, v54
	v_lshlrev_b64 v[56:57], 10, v[54:55]
	v_lshlrev_b64 v[54:55], 11, v[54:55]
	v_lshl_add_u64 v[56:57], v[20:21], 0, v[56:57]
	v_lshl_add_u64 v[54:55], v[22:23], 0, v[54:55]
	global_load_dword v58, v[56:57], off
	global_load_dword v59, v[54:55], off offset:512
	v_lshlrev_b32_e32 v10, 16, v11
	v_and_b32_e32 v11, 0xffff0000, v11
	v_pk_mul_f32 v[52:53], v[38:39], v[38:39]
	v_cmp_lt_i32_e32 vcc, s46, v0
	v_pk_mul_f32 v[50:51], v[10:11], v[10:11]
	v_mov_b32_e32 v18, v0
	v_add_f32_e32 v0, v52, v53
	v_lshlrev_b32_e32 v40, 16, v12
	v_and_b32_e32 v41, 0xffff0000, v12
	v_add_f32_e32 v0, v50, v0
	v_pk_mul_f32 v[48:49], v[40:41], v[40:41]
	v_add_f32_e32 v0, v51, v0
	v_lshlrev_b32_e32 v12, 16, v13
	v_and_b32_e32 v13, 0xffff0000, v13
	v_add_f32_e32 v0, v48, v0
	v_lshlrev_b32_e32 v42, 16, v17
	v_and_b32_e32 v43, 0xffff0000, v17
	v_lshlrev_b32_e32 v44, 16, v16
	v_and_b32_e32 v45, 0xffff0000, v16
	v_lshlrev_b32_e32 v16, 16, v15
	v_and_b32_e32 v17, 0xffff0000, v15
	v_lshlrev_b32_e32 v46, 16, v14
	v_and_b32_e32 v47, 0xffff0000, v14
	v_pk_mul_f32 v[14:15], v[12:13], v[12:13]
	v_add_f32_e32 v0, v49, v0
	v_add_f32_e32 v0, v14, v0
	v_add_f32_e32 v0, v15, v0
	ds_bpermute_b32 v14, v19, v0
	s_or_b64 s[2:3], vcc, s[2:3]
	s_waitcnt lgkmcnt(0)
	v_add_f32_e32 v0, v0, v14
	ds_bpermute_b32 v14, v26, v0
	s_waitcnt lgkmcnt(0)
	v_add_f32_e32 v0, v0, v14
	ds_bpermute_b32 v14, v27, v0
	s_waitcnt lgkmcnt(0)
	v_add_f32_e32 v0, v0, v14
	ds_bpermute_b32 v14, v28, v0
	s_waitcnt lgkmcnt(0)
	v_add_f32_e32 v0, v0, v14
	v_fmamk_f32 v0, v0, 0x3c000000, v227
	v_mul_f32_e32 v14, 0x4b800000, v0
	v_cmp_gt_f32_e32 vcc, s14, v0
	s_nop 1
	v_cndmask_b32_e32 v0, v0, v14, vcc
	v_rsq_f32_e32 v0, v0
	s_nop 0
	v_mul_f32_e32 v14, 0x45800000, v0
	v_cndmask_b32_e32 v0, v0, v14, vcc
	v_pk_mul_f32 v[14:15], v[0:1], v[38:39] op_sel_hi:[0,1]
	v_pk_mul_f32 v[10:11], v[0:1], v[10:11] op_sel_hi:[0,1]
	v_pk_mul_f32 v[38:39], v[0:1], v[40:41] op_sel_hi:[0,1]
	v_pk_mul_f32 v[12:13], v[0:1], v[12:13] op_sel_hi:[0,1]
	v_pk_mul_f32 v[14:15], v[6:7], v[14:15]
	v_pk_mul_f32 v[10:11], v[8:9], v[10:11]
	v_pk_mul_f32 v[38:39], v[2:3], v[38:39]
	v_pk_mul_f32 v[12:13], v[4:5], v[12:13]
	v_pk_mul_f32 v[14:15], v[14:15], v[46:47]
	v_pk_mul_f32 v[16:17], v[10:11], v[16:17]
	v_pk_mul_f32 v[38:39], v[38:39], v[44:45]
	v_pk_mul_f32 v[40:41], v[12:13], v[42:43]
	v_cvt_pk_bf16_f32 v10, v14, v15
	v_cvt_pk_bf16_f32 v11, v16, v17
	v_cvt_pk_bf16_f32 v12, v38, v39
	v_cvt_pk_bf16_f32 v13, v40, v41
	global_store_dwordx4 v[24:25], v[10:13], off
	v_lshl_add_u64 v[24:25], v[24:25], 0, s[44:45]
	s_waitcnt vmcnt(3)
	v_mov_b64_e32 v[16:17], v[36:37]
	v_mov_b64_e32 v[12:13], v[32:33]
	v_mov_b64_e32 v[10:11], v[30:31]
	v_mov_b64_e32 v[14:15], v[34:35]
	s_andn2_b64 exec, exec, s[2:3]
	s_cbranch_execnz .LBB0_86
